# in-proj L0 free-slack start delay spread over four offsets (2/4/6/8 sleeps by CU&3)
# speedup vs baseline: 1.0065x; 1.0065x over previous
; __global__ void __launch_bounds__(512, 2) mega(P p) {
;     ...
;       const int l = (ph - 2) >> 2, s = (ph - 2) & 3;
;       if (s == 0) { for (int rr = 0; rr < REP_INPROJ; ++rr) { if (rr) cg::this_grid().sync(); phase_inproj(p, l, lds); } }
.LBB0_74:
	s_andn2_b64 vcc, exec, s[0:1]
	s_cbranch_vccnz .LBB0_941
	s_cmp_lg_u32 s24, 1
	s_mov_b64 s[0:1], -1
	s_cbranch_scc0 .LBB0_812
	v_readlane_b32 s0, v254, 9
	v_readlane_b32 s1, v254, 10
	v_mov_b32_e32 v0, v195
	s_andn2_b64 vcc, exec, s[0:1]
	s_cbranch_vccnz .LBB0_811
	s_cmp_lg_u32 s50, 0
	s_cbranch_scc1 .Ldephase_in_done
	s_cmp_lt_u32 s84, 14
	s_cbranch_scc1 .Ldephase_in_done
	s_and_b32 s100, s84, 3
	s_add_i32 s100, s100, 1
	s_lshl_b32 s100, s100, 1
.Ldephase_in_loop:
	s_sleep 127
	s_sub_i32 s100, s100, 1
	s_cmp_lg_u32 s100, 0
	s_cbranch_scc1 .Ldephase_in_loop
